# static s_setprio 1 for waves 4-7 only inside the two GEMM phases (set at unit header, cleared at phase exit); no per-phase flips; attention at equal priority
# speedup vs baseline: 1.0014x; 1.0014x over previous
; #define PG8_STAGE(bufoff, gbase, voff) do { _Pragma("unroll") for (int _i = 0; _i < 2; ++_i) \
;         __builtin_amdgcn_global_load_lds((const unsigned*)((const char*)(gbase) + (voff)[_i]), (LAS unsigned*)(lds + (bufoff) + ldsw + _i * 8192), 16, 0, 0); } while (0)
; #define PG8_LDA(dst, b, h) do { _Pragma("unroll") for (int m = 0; m < 4; ++m) _Pragma("unroll") for (int k = 0; k < 2; ++k) dst[m][k] = *(const LAS bf16x8*)(lds + PG8_SA(b, h) + aoff + m * 2048 + k * 1024); } while (0)
; #define PG8_LDB(dst, b, h) do { _Pragma("unroll") for (int n = 0; n < 2; ++n) _Pragma("unroll") for (int k = 0; k < 2; ++k) dst[n][k] = *(const LAS bf16x8*)(lds + PG8_SB(b, h) + boff + n * 2048 + k * 1024); } while (0)
; #define PG8_MMA(ai, bj, At, Bt_) do { __builtin_amdgcn_s_setprio(1); _Pragma("unroll") for (int m = 0; m < 4; ++m) _Pragma("unroll") for (int n = 0; n < 2; ++n) _Pragma("unroll") for (int k = 0; k < 2; ++k) \
;         acc[ai][bj][m][n] = __builtin_amdgcn_mfma_f32_16x16x32_bf16(Bt_[n][k], At[m][k], acc[ai][bj][m][n], 0, 0, 0); __builtin_amdgcn_s_setprio(0); } while (0)
; #define PG8_WAIT_L(n) asm volatile("s_waitcnt lgkmcnt(" #n ")" ::: "memory")
; #define PG8_BAR __builtin_amdgcn_s_barrier()
; template <bool REMAP>
; DI void gemm_phase(LAS unsigned char* lds, const u16* A, int lda, const u16* Bt, int K, u16* O, int ldc, int nunits) {
;     ...
;         const bool has_next = next_unit(ui + 1, nunits, nxt);
;         const char* nA = has_next ? (const char*)A + (size_t)nxt.pm * tstepA : cA; const char* nB = has_next ? (const char*)Bt + (size_t)nxt.pn * tstepB : cB;
;         for (int t = 0; t < nt; t += 2) {
;             const bool last = (t == nt - 2);
;             const char* a1 = cA + akb(t + 1);
;             const char* a2 = last ? nA + akb(0) : cA + akb(t + 2); const char* b2 = last ? nB : cB + (size_t)(t + 2) * kstep;
;             const char* a3 = last ? nA + akb(1) : cA + akb(t + 3); const char* b3 = b2 + kstep;
;             PG8_LDB(B0, 0, 0); PG8_SCHED; PG8_LDA(At, 0, 0); PG8_STAGE(PG8_SA(1, 1), a1 + hstepA, voffA);
;             PG8_WAIT_L(8); PG8_BAR; PG8_WAIT_L(0); PG8_MMA(0, 0, At, B0); PG8_BAR; PG8_SCHED;
;             PG8_LDB(B1, 0, 1); PG8_STAGE(PG8_SB(0, 0), b2, voffB);
;             PG8_BAR; PG8_WAIT_L(0); PG8_MMA(0, 1, At, B1); PG8_BAR;
;             PG8_LDA(At, 0, 1); PG8_STAGE(PG8_SA(0, 0), a2, voffA);
.LBB0_136:
	s_ashr_i32 s5, s4, 31
	s_lshl_b64 s[12:13], s[4:5], 19
	s_add_u32 s12, s3, s12
	s_addc_u32 s13, s24, s13
	s_and_b64 s[14:15], s[22:23], exec
	s_cselect_b32 s5, s13, s11
	s_cselect_b32 s46, s12, s10
	s_ashr_i32 s7, s6, 31
	s_lshl_b64 s[14:15], s[6:7], 19
	s_add_u32 s14, s16, s14
	s_addc_u32 s15, s25, s15
	s_and_b64 s[22:23], s[22:23], exec
	s_cselect_b32 s7, s15, s21
	s_cselect_b32 s47, s14, s20
	s_add_u32 s49, s46, 0x80
	s_addc_u32 s50, s5, 0
	s_add_u32 s51, s20, 0x100
	s_addc_u32 s54, s21, 0
	s_add_u32 s22, s10, 0x40080
	s_addc_u32 s23, s11, 0
	s_mov_b32 s55, -2
	s_mov_b64 s[20:21], 0
	s_cmp_ge_u32 s27, 0x1000
	s_cbranch_scc0 .Lg1_noprio
	s_setprio 1
.Lg1_noprio:
	v_lshl_add_u64 v[140:141], s[22:23], 0, v[136:137]
	v_lshl_add_u64 v[142:143], s[22:23], 0, v[138:139]
	s_add_u32 s22, s10, s20
	s_addc_u32 s23, s11, s21
	s_add_u32 s30, s22, 0x100
	s_addc_u32 s31, s23, 0
	s_add_u32 s56, s51, s20
	s_addc_u32 s57, s54, s21
	s_add_u32 s22, s22, 0x180
	s_addc_u32 s23, s23, 0
	s_add_i32 s58, 0, 0x10000
	v_add_u32_e32 v160, s58, v145
	ds_read_b128 v[148:151], v160
	ds_read_b128 v[152:155], v160 offset:1024
	ds_read_b128 v[156:159], v160 offset:2048
	ds_read_b128 v[160:163], v160 offset:3072
	s_cmpk_eq_i32 s20, 0x700
	s_cselect_b32 s29, s50, s23
	s_cselect_b32 s28, s49, s22
	s_cselect_b32 s23, s7, s57
	s_cselect_b32 s22, s47, s56
	s_cselect_b32 s31, s5, s31
	s_cselect_b32 s30, s46, s30
	v_lshl_add_u64 v[172:173], v[142:143], 0, s[20:21]
	s_add_i32 m0, s27, 0xc000
	ds_read_b128 v[164:167], v147
	ds_read_b128 v[168:171], v147 offset:1024
	ds_read_b128 v[192:195], v147 offset:2048
	ds_read_b128 v[196:199], v147 offset:3072
	ds_read_b128 v[200:203], v147 offset:4096
	ds_read_b128 v[204:207], v147 offset:5120
	ds_read_b128 v[208:211], v147 offset:6144
	ds_read_b128 v[212:215], v147 offset:7168
	global_load_lds_dwordx4 v[172:173], off
	v_lshl_add_u64 v[172:173], v[140:141], 0, s[20:21]
	s_add_i32 m0, s27, 0xe000
	s_nop 0
	global_load_lds_dwordx4 v[172:173], off
	s_waitcnt lgkmcnt(8)
	s_barrier
	s_waitcnt lgkmcnt(0)
	s_waitcnt lgkmcnt(0)
	v_mfma_f32_16x16x32_bf16 v[126:129], v[148:151], v[164:167], 0
	v_mfma_f32_16x16x32_bf16 v[122:125], v[156:159], v[164:167], 0
	v_mfma_f32_16x16x32_bf16 v[118:121], v[148:151], v[192:195], 0
	v_mfma_f32_16x16x32_bf16 v[114:117], v[156:159], v[192:195], 0
	v_mfma_f32_16x16x32_bf16 v[102:105], v[148:151], v[200:203], 0
	v_mfma_f32_16x16x32_bf16 v[98:101], v[156:159], v[200:203], 0
	v_mfma_f32_16x16x32_bf16 v[86:89], v[148:151], v[208:211], 0
	v_mfma_f32_16x16x32_bf16 v[82:85], v[156:159], v[208:211], 0
	v_mfma_f32_16x16x32_bf16 v[126:129], v[152:155], v[168:171], v[126:129]
	v_mfma_f32_16x16x32_bf16 v[122:125], v[160:163], v[168:171], v[122:125]
	v_mfma_f32_16x16x32_bf16 v[118:121], v[152:155], v[196:199], v[118:121]
	v_mfma_f32_16x16x32_bf16 v[114:117], v[160:163], v[196:199], v[114:117]
	v_mfma_f32_16x16x32_bf16 v[102:105], v[152:155], v[204:207], v[102:105]
	v_mfma_f32_16x16x32_bf16 v[98:101], v[160:163], v[204:207], v[98:101]
	v_mfma_f32_16x16x32_bf16 v[86:89], v[152:155], v[212:215], v[86:89]
	v_mfma_f32_16x16x32_bf16 v[82:85], v[160:163], v[212:215], v[82:85]
	s_barrier
	s_add_i32 s59, 0, 0x14000
	v_add_u32_e32 v172, s59, v145
	s_add_i32 s56, s58, s26
	ds_read_b128 v[216:219], v172
	ds_read_b128 v[220:223], v172 offset:1024
	ds_read_b128 v[224:227], v172 offset:2048
	ds_read_b128 v[228:231], v172 offset:3072
	v_lshl_add_u64 v[172:173], s[22:23], 0, v[0:1]
	s_mov_b32 m0, s56
	v_lshl_add_u64 v[232:233], s[22:23], 0, v[130:131]
	global_load_lds_dwordx4 v[172:173], off
	s_add_i32 m0, s56, 0x2000
	s_nop 0
	global_load_lds_dwordx4 v[232:233], off
	s_barrier
	s_waitcnt lgkmcnt(0)
	s_waitcnt lgkmcnt(0)
	v_mfma_f32_16x16x32_bf16 v[110:113], v[216:219], v[164:167], 0
	v_mfma_f32_16x16x32_bf16 v[106:109], v[224:227], v[164:167], 0
	v_mfma_f32_16x16x32_bf16 v[94:97], v[216:219], v[192:195], 0
	v_mfma_f32_16x16x32_bf16 v[90:93], v[224:227], v[192:195], 0
	v_mfma_f32_16x16x32_bf16 v[78:81], v[216:219], v[200:203], 0
	v_mfma_f32_16x16x32_bf16 v[74:77], v[224:227], v[200:203], 0
	v_mfma_f32_16x16x32_bf16 v[70:73], v[216:219], v[208:211], 0
	v_mfma_f32_16x16x32_bf16 v[66:69], v[224:227], v[208:211], 0
	v_mfma_f32_16x16x32_bf16 v[110:113], v[220:223], v[168:171], v[110:113]
	v_mfma_f32_16x16x32_bf16 v[106:109], v[228:231], v[168:171], v[106:109]
	v_mfma_f32_16x16x32_bf16 v[94:97], v[220:223], v[196:199], v[94:97]
	v_mfma_f32_16x16x32_bf16 v[90:93], v[228:231], v[196:199], v[90:93]
	v_mfma_f32_16x16x32_bf16 v[78:81], v[220:223], v[204:207], v[78:81]
	v_mfma_f32_16x16x32_bf16 v[74:77], v[228:231], v[204:207], v[74:77]
	v_mfma_f32_16x16x32_bf16 v[70:73], v[220:223], v[212:215], v[70:73]
	v_mfma_f32_16x16x32_bf16 v[66:69], v[228:231], v[212:215], v[66:69]
	s_mov_b32 m0, s27
	v_lshl_add_u64 v[234:235], s[30:31], 0, v[134:135]
	s_barrier
	ds_read_b128 v[164:167], v147 offset:16384
	ds_read_b128 v[168:171], v147 offset:17408
	ds_read_b128 v[192:195], v147 offset:18432
	ds_read_b128 v[196:199], v147 offset:19456
	ds_read_b128 v[200:203], v147 offset:20480
	ds_read_b128 v[204:207], v147 offset:21504
	ds_read_b128 v[208:211], v147 offset:22528
	ds_read_b128 v[212:215], v147 offset:23552
	global_load_lds_dwordx4 v[234:235], off
	v_lshl_add_u64 v[234:235], s[30:31], 0, v[132:133]
	s_mov_b32 m0, s34
	s_nop 0
	global_load_lds_dwordx4 v[234:235], off
	s_barrier
; #define PG8_STAGE(bufoff, gbase, voff) do { _Pragma("unroll") for (int _i = 0; _i < 2; ++_i) \
;         __builtin_amdgcn_global_load_lds((const unsigned*)((const char*)(gbase) + (voff)[_i]), (LAS unsigned*)(lds + (bufoff) + ldsw + _i * 8192), 16, 0, 0); } while (0)
; #define PG8_LDA(dst, b, h) do { _Pragma("unroll") for (int m = 0; m < 4; ++m) _Pragma("unroll") for (int k = 0; k < 2; ++k) dst[m][k] = *(const LAS bf16x8*)(lds + PG8_SA(b, h) + aoff + m * 2048 + k * 1024); } while (0)
; #define PG8_LDB(dst, b, h) do { _Pragma("unroll") for (int n = 0; n < 2; ++n) _Pragma("unroll") for (int k = 0; k < 2; ++k) dst[n][k] = *(const LAS bf16x8*)(lds + PG8_SB(b, h) + boff + n * 2048 + k * 1024); } while (0)
; #define PG8_MMA(ai, bj, At, Bt_) do { __builtin_amdgcn_s_setprio(1); _Pragma("unroll") for (int m = 0; m < 4; ++m) _Pragma("unroll") for (int n = 0; n < 2; ++n) _Pragma("unroll") for (int k = 0; k < 2; ++k) \
;         acc[ai][bj][m][n] = __builtin_amdgcn_mfma_f32_16x16x32_bf16(Bt_[n][k], At[m][k], acc[ai][bj][m][n], 0, 0, 0); __builtin_amdgcn_s_setprio(0); } while (0)
; #define PG8_WAIT_V(n) asm volatile("s_waitcnt vmcnt(" #n ")" ::: "memory")
; #define PG8_WAIT_L(n) asm volatile("s_waitcnt lgkmcnt(" #n ")" ::: "memory")
; #define PG8_BAR __builtin_amdgcn_s_barrier()
; #define PG8_SCHED __builtin_amdgcn_sched_barrier(0)
; template <bool REMAP>
; DI void gemm_phase(LAS unsigned char* lds, const u16* A, int lda, const u16* Bt, int K, u16* O, int ldc, int nunits) {
;     ...
;             PG8_BAR; PG8_WAIT_L(0); PG8_MMA(1, 0, At, B0); PG8_BAR; PG8_SCHED;
;             PG8_STAGE(PG8_SB(0, 1), b2 + hstepB, voffB);
;             PG8_WAIT_V(6); PG8_BAR; PG8_MMA(1, 1, At, B1); PG8_BAR;
;             PG8_LDB(B0, 1, 0); PG8_SCHED; PG8_LDA(At, 1, 0); PG8_STAGE(PG8_SA(0, 1), a2 + hstepA, voffA);
;             PG8_WAIT_L(8); PG8_BAR; PG8_WAIT_L(0); PG8_MMA(0, 0, At, B0); PG8_BAR; PG8_SCHED;
;             PG8_LDB(B1, 1, 1); PG8_STAGE(PG8_SB(1, 0), b3, voffB);
	s_waitcnt lgkmcnt(0)
	s_waitcnt lgkmcnt(0)
	v_mfma_f32_16x16x32_bf16 v[62:65], v[148:151], v[164:167], 0
	v_mfma_f32_16x16x32_bf16 v[58:61], v[156:159], v[164:167], 0
	v_mfma_f32_16x16x32_bf16 v[54:57], v[148:151], v[192:195], 0
	v_mfma_f32_16x16x32_bf16 v[50:53], v[156:159], v[192:195], 0
	v_mfma_f32_16x16x32_bf16 v[38:41], v[148:151], v[200:203], 0
	v_mfma_f32_16x16x32_bf16 v[34:37], v[156:159], v[200:203], 0
	v_mfma_f32_16x16x32_bf16 v[22:25], v[148:151], v[208:211], 0
	v_mfma_f32_16x16x32_bf16 v[18:21], v[156:159], v[208:211], 0
	v_mfma_f32_16x16x32_bf16 v[62:65], v[152:155], v[168:171], v[62:65]
	v_mfma_f32_16x16x32_bf16 v[58:61], v[160:163], v[168:171], v[58:61]
	v_mfma_f32_16x16x32_bf16 v[54:57], v[152:155], v[196:199], v[54:57]
	v_mfma_f32_16x16x32_bf16 v[50:53], v[160:163], v[196:199], v[50:53]
	v_mfma_f32_16x16x32_bf16 v[38:41], v[152:155], v[204:207], v[38:41]
	v_mfma_f32_16x16x32_bf16 v[34:37], v[160:163], v[204:207], v[34:37]
	v_mfma_f32_16x16x32_bf16 v[22:25], v[152:155], v[212:215], v[22:25]
	v_mfma_f32_16x16x32_bf16 v[18:21], v[160:163], v[212:215], v[18:21]
	s_barrier
	s_add_u32 s56, s22, 0x40000
	s_addc_u32 s57, s23, 0
	s_add_i32 s58, s59, s26
	v_lshl_add_u64 v[148:149], s[56:57], 0, v[0:1]
	s_mov_b32 m0, s58
	s_nop 0
	global_load_lds_dwordx4 v[148:149], off
	v_lshl_add_u64 v[148:149], s[56:57], 0, v[130:131]
	s_add_i32 m0, s58, 0x2000
	s_nop 0
	global_load_lds_dwordx4 v[148:149], off
	s_waitcnt vmcnt(6)
	s_barrier
	v_mfma_f32_16x16x32_bf16 v[46:49], v[216:219], v[164:167], 0
	v_mfma_f32_16x16x32_bf16 v[42:45], v[224:227], v[164:167], 0
	v_mfma_f32_16x16x32_bf16 v[30:33], v[216:219], v[192:195], 0
	v_mfma_f32_16x16x32_bf16 v[26:29], v[224:227], v[192:195], 0
	v_mfma_f32_16x16x32_bf16 v[14:17], v[216:219], v[200:203], 0
	v_mfma_f32_16x16x32_bf16 v[10:13], v[224:227], v[200:203], 0
	v_mfma_f32_16x16x32_bf16 v[6:9], v[216:219], v[208:211], 0
	v_mfma_f32_16x16x32_bf16 v[2:5], v[224:227], v[208:211], 0
	v_mfma_f32_16x16x32_bf16 v[46:49], v[220:223], v[168:171], v[46:49]
	v_mfma_f32_16x16x32_bf16 v[42:45], v[228:231], v[168:171], v[42:45]
	v_mfma_f32_16x16x32_bf16 v[30:33], v[220:223], v[196:199], v[30:33]
	v_mfma_f32_16x16x32_bf16 v[26:29], v[228:231], v[196:199], v[26:29]
	v_mfma_f32_16x16x32_bf16 v[14:17], v[220:223], v[204:207], v[14:17]
	v_mfma_f32_16x16x32_bf16 v[10:13], v[228:231], v[204:207], v[10:13]
	v_mfma_f32_16x16x32_bf16 v[6:9], v[220:223], v[212:215], v[6:9]
	v_mfma_f32_16x16x32_bf16 v[2:5], v[228:231], v[212:215], v[2:5]
	s_add_i32 s56, 0, 0x18000
	v_add_u32_e32 v160, s56, v145
	s_barrier
	ds_read_b128 v[148:151], v160
	ds_read_b128 v[152:155], v160 offset:1024
	ds_read_b128 v[156:159], v160 offset:2048
	ds_read_b128 v[160:163], v160 offset:3072
	s_add_u32 s30, s30, 0x40000
	s_addc_u32 s31, s31, 0
	s_mov_b32 m0, s35
	v_lshl_add_u64 v[216:217], s[30:31], 0, v[134:135]
	ds_read_b128 v[164:167], v147 offset:32768
	ds_read_b128 v[168:171], v147 offset:33792
	ds_read_b128 v[192:195], v147 offset:34816
	ds_read_b128 v[196:199], v147 offset:35840
	ds_read_b128 v[200:203], v147 offset:36864
	ds_read_b128 v[204:207], v147 offset:37888
	ds_read_b128 v[208:211], v147 offset:38912
	ds_read_b128 v[212:215], v147 offset:39936
	global_load_lds_dwordx4 v[216:217], off
	v_lshl_add_u64 v[216:217], s[30:31], 0, v[132:133]
	s_mov_b32 m0, s36
	s_nop 0
	global_load_lds_dwordx4 v[216:217], off
	s_waitcnt lgkmcnt(8)
	s_barrier
	s_waitcnt lgkmcnt(0)
	s_waitcnt lgkmcnt(0)
	v_mfma_f32_16x16x32_bf16 v[126:129], v[148:151], v[164:167], v[126:129]
	v_mfma_f32_16x16x32_bf16 v[122:125], v[156:159], v[164:167], v[122:125]
	v_mfma_f32_16x16x32_bf16 v[118:121], v[148:151], v[192:195], v[118:121]
	v_mfma_f32_16x16x32_bf16 v[114:117], v[156:159], v[192:195], v[114:117]
	v_mfma_f32_16x16x32_bf16 v[102:105], v[148:151], v[200:203], v[102:105]
	v_mfma_f32_16x16x32_bf16 v[98:101], v[156:159], v[200:203], v[98:101]
	v_mfma_f32_16x16x32_bf16 v[86:89], v[148:151], v[208:211], v[86:89]
	v_mfma_f32_16x16x32_bf16 v[82:85], v[156:159], v[208:211], v[82:85]
	v_mfma_f32_16x16x32_bf16 v[126:129], v[152:155], v[168:171], v[126:129]
	v_mfma_f32_16x16x32_bf16 v[122:125], v[160:163], v[168:171], v[122:125]
	v_mfma_f32_16x16x32_bf16 v[118:121], v[152:155], v[196:199], v[118:121]
	v_mfma_f32_16x16x32_bf16 v[114:117], v[160:163], v[196:199], v[114:117]
	v_mfma_f32_16x16x32_bf16 v[102:105], v[152:155], v[204:207], v[102:105]
	v_mfma_f32_16x16x32_bf16 v[98:101], v[160:163], v[204:207], v[98:101]
	v_mfma_f32_16x16x32_bf16 v[86:89], v[152:155], v[212:215], v[86:89]
	v_mfma_f32_16x16x32_bf16 v[82:85], v[160:163], v[212:215], v[82:85]
	s_barrier
; #define PG8_STAGE(bufoff, gbase, voff) do { _Pragma("unroll") for (int _i = 0; _i < 2; ++_i) \
;         __builtin_amdgcn_global_load_lds((const unsigned*)((const char*)(gbase) + (voff)[_i]), (LAS unsigned*)(lds + (bufoff) + ldsw + _i * 8192), 16, 0, 0); } while (0)
; #define PG8_LDA(dst, b, h) do { _Pragma("unroll") for (int m = 0; m < 4; ++m) _Pragma("unroll") for (int k = 0; k < 2; ++k) dst[m][k] = *(const LAS bf16x8*)(lds + PG8_SA(b, h) + aoff + m * 2048 + k * 1024); } while (0)
; #define PG8_LDB(dst, b, h) do { _Pragma("unroll") for (int n = 0; n < 2; ++n) _Pragma("unroll") for (int k = 0; k < 2; ++k) dst[n][k] = *(const LAS bf16x8*)(lds + PG8_SB(b, h) + boff + n * 2048 + k * 1024); } while (0)
; #define PG8_MMA(ai, bj, At, Bt_) do { __builtin_amdgcn_s_setprio(1); _Pragma("unroll") for (int m = 0; m < 4; ++m) _Pragma("unroll") for (int n = 0; n < 2; ++n) _Pragma("unroll") for (int k = 0; k < 2; ++k) \
;         acc[ai][bj][m][n] = __builtin_amdgcn_mfma_f32_16x16x32_bf16(Bt_[n][k], At[m][k], acc[ai][bj][m][n], 0, 0, 0); __builtin_amdgcn_s_setprio(0); } while (0)
; #define PG8_WAIT_V(n) asm volatile("s_waitcnt vmcnt(" #n ")" ::: "memory")
; #define PG8_WAIT_L(n) asm volatile("s_waitcnt lgkmcnt(" #n ")" ::: "memory")
; #define PG8_BAR __builtin_amdgcn_s_barrier()
; #define PG8_SCHED __builtin_amdgcn_sched_barrier(0)
; template <bool REMAP>
; DI void gemm_phase(LAS unsigned char* lds, const u16* A, int lda, const u16* Bt, int K, u16* O, int ldc, int nunits) {
;     ...
;             PG8_LDB(B1, 1, 1); PG8_STAGE(PG8_SB(1, 0), b3, voffB);
;             PG8_BAR; PG8_WAIT_L(0); PG8_MMA(0, 1, At, B1); PG8_BAR;
;             PG8_LDA(At, 1, 1); PG8_STAGE(PG8_SA(1, 0), a3, voffA);
;             PG8_BAR; PG8_WAIT_L(0); PG8_MMA(1, 0, At, B0); PG8_BAR; PG8_SCHED;
;             PG8_STAGE(PG8_SB(1, 1), b3 + hstepB, voffB);
;             PG8_WAIT_V(6); PG8_BAR; PG8_MMA(1, 1, At, B1); PG8_BAR;
	s_add_i32 s30, 0, 0x1c000
	s_add_i32 s31, s56, s26
	v_add_u32_e32 v228, s30, v145
	v_lshl_add_u64 v[172:173], v[172:173], 0, s[18:19]
	s_mov_b32 m0, s31
	ds_read_b128 v[216:219], v228
	ds_read_b128 v[220:223], v228 offset:1024
	ds_read_b128 v[224:227], v228 offset:2048
	ds_read_b128 v[228:231], v228 offset:3072
	global_load_lds_dwordx4 v[172:173], off
	v_lshl_add_u64 v[172:173], v[232:233], 0, s[18:19]
	s_add_i32 m0, s31, 0x2000
	s_nop 0
	global_load_lds_dwordx4 v[172:173], off
	s_barrier
	s_waitcnt lgkmcnt(0)
	s_waitcnt lgkmcnt(0)
	v_mfma_f32_16x16x32_bf16 v[110:113], v[216:219], v[164:167], v[110:113]
	v_mfma_f32_16x16x32_bf16 v[106:109], v[224:227], v[164:167], v[106:109]
	v_mfma_f32_16x16x32_bf16 v[94:97], v[216:219], v[192:195], v[94:97]
	v_mfma_f32_16x16x32_bf16 v[90:93], v[224:227], v[192:195], v[90:93]
	v_mfma_f32_16x16x32_bf16 v[78:81], v[216:219], v[200:203], v[78:81]
	v_mfma_f32_16x16x32_bf16 v[74:77], v[224:227], v[200:203], v[74:77]
	v_mfma_f32_16x16x32_bf16 v[70:73], v[216:219], v[208:211], v[70:73]
	v_mfma_f32_16x16x32_bf16 v[66:69], v[224:227], v[208:211], v[66:69]
	v_mfma_f32_16x16x32_bf16 v[110:113], v[220:223], v[168:171], v[110:113]
	v_mfma_f32_16x16x32_bf16 v[106:109], v[228:231], v[168:171], v[106:109]
	v_mfma_f32_16x16x32_bf16 v[94:97], v[220:223], v[196:199], v[94:97]
	v_mfma_f32_16x16x32_bf16 v[90:93], v[228:231], v[196:199], v[90:93]
	v_mfma_f32_16x16x32_bf16 v[78:81], v[220:223], v[204:207], v[78:81]
	v_mfma_f32_16x16x32_bf16 v[74:77], v[228:231], v[204:207], v[74:77]
	v_mfma_f32_16x16x32_bf16 v[70:73], v[220:223], v[212:215], v[70:73]
	v_mfma_f32_16x16x32_bf16 v[66:69], v[228:231], v[212:215], v[66:69]
	s_mov_b32 m0, s37
	v_lshl_add_u64 v[172:173], s[28:29], 0, v[134:135]
	s_barrier
	ds_read_b128 v[164:167], v147 offset:49152
	ds_read_b128 v[168:171], v147 offset:50176
	ds_read_b128 v[192:195], v147 offset:51200
	ds_read_b128 v[196:199], v147 offset:52224
	ds_read_b128 v[200:203], v147 offset:53248
	ds_read_b128 v[204:207], v147 offset:54272
	ds_read_b128 v[208:211], v147 offset:55296
	ds_read_b128 v[212:215], v147 offset:56320
	global_load_lds_dwordx4 v[172:173], off
	v_lshl_add_u64 v[172:173], s[28:29], 0, v[132:133]
	s_mov_b32 m0, s38
	s_nop 0
	global_load_lds_dwordx4 v[172:173], off
	s_barrier
	s_waitcnt lgkmcnt(0)
	s_waitcnt lgkmcnt(0)
	v_mfma_f32_16x16x32_bf16 v[62:65], v[148:151], v[164:167], v[62:65]
	v_mfma_f32_16x16x32_bf16 v[58:61], v[156:159], v[164:167], v[58:61]
	v_mfma_f32_16x16x32_bf16 v[54:57], v[148:151], v[192:195], v[54:57]
	v_mfma_f32_16x16x32_bf16 v[50:53], v[156:159], v[192:195], v[50:53]
	v_mfma_f32_16x16x32_bf16 v[38:41], v[148:151], v[200:203], v[38:41]
	v_mfma_f32_16x16x32_bf16 v[34:37], v[156:159], v[200:203], v[34:37]
	v_mfma_f32_16x16x32_bf16 v[22:25], v[148:151], v[208:211], v[22:25]
	v_mfma_f32_16x16x32_bf16 v[18:21], v[156:159], v[208:211], v[18:21]
	v_mfma_f32_16x16x32_bf16 v[62:65], v[152:155], v[168:171], v[62:65]
	v_mfma_f32_16x16x32_bf16 v[58:61], v[160:163], v[168:171], v[58:61]
	v_mfma_f32_16x16x32_bf16 v[54:57], v[152:155], v[196:199], v[54:57]
	v_mfma_f32_16x16x32_bf16 v[50:53], v[160:163], v[196:199], v[50:53]
	v_mfma_f32_16x16x32_bf16 v[38:41], v[152:155], v[204:207], v[38:41]
	v_mfma_f32_16x16x32_bf16 v[34:37], v[160:163], v[204:207], v[34:37]
	v_mfma_f32_16x16x32_bf16 v[22:25], v[152:155], v[212:215], v[22:25]
	v_mfma_f32_16x16x32_bf16 v[18:21], v[160:163], v[212:215], v[18:21]
	s_barrier
	s_add_u32 s22, s22, 0x40080
	s_addc_u32 s23, s23, 0
	s_add_i32 s28, s30, s26
	v_lshl_add_u64 v[148:149], s[22:23], 0, v[0:1]
	s_mov_b32 m0, s28
	s_nop 0
	global_load_lds_dwordx4 v[148:149], off
	v_lshl_add_u64 v[148:149], s[22:23], 0, v[130:131]
	s_add_i32 m0, s28, 0x2000
	s_nop 0
	global_load_lds_dwordx4 v[148:149], off
	s_waitcnt vmcnt(6)
	s_barrier
	v_mfma_f32_16x16x32_bf16 v[46:49], v[216:219], v[164:167], v[46:49]
	v_mfma_f32_16x16x32_bf16 v[42:45], v[224:227], v[164:167], v[42:45]
	v_mfma_f32_16x16x32_bf16 v[30:33], v[216:219], v[192:195], v[30:33]
	v_mfma_f32_16x16x32_bf16 v[26:29], v[224:227], v[192:195], v[26:29]
	v_mfma_f32_16x16x32_bf16 v[14:17], v[216:219], v[200:203], v[14:17]
	v_mfma_f32_16x16x32_bf16 v[10:13], v[224:227], v[200:203], v[10:13]
	v_mfma_f32_16x16x32_bf16 v[6:9], v[216:219], v[208:211], v[6:9]
	v_mfma_f32_16x16x32_bf16 v[2:5], v[224:227], v[208:211], v[2:5]
	v_mfma_f32_16x16x32_bf16 v[46:49], v[220:223], v[168:171], v[46:49]
	v_mfma_f32_16x16x32_bf16 v[42:45], v[228:231], v[168:171], v[42:45]
	v_mfma_f32_16x16x32_bf16 v[30:33], v[220:223], v[196:199], v[30:33]
	v_mfma_f32_16x16x32_bf16 v[26:29], v[228:231], v[196:199], v[26:29]
	v_mfma_f32_16x16x32_bf16 v[14:17], v[220:223], v[204:207], v[14:17]
	v_mfma_f32_16x16x32_bf16 v[10:13], v[228:231], v[204:207], v[10:13]
	v_mfma_f32_16x16x32_bf16 v[6:9], v[220:223], v[212:215], v[6:9]
	v_mfma_f32_16x16x32_bf16 v[2:5], v[228:231], v[212:215], v[2:5]
	s_add_i32 s55, s55, 2
	s_add_u32 s20, s20, 0x100
	s_addc_u32 s21, s21, 0
	s_cmp_gt_u32 s55, 13
	s_barrier

; #define PG8_WAIT_V(n) asm volatile("s_waitcnt vmcnt(" #n ")" ::: "memory")
; #define PG8_BAR __builtin_amdgcn_s_barrier()
; template <bool REMAP>
; DI void gemm_phase(LAS unsigned char* lds, const u16* A, int lda, const u16* Bt, int K, u16* O, int ldc, int nunits) {
;     ...
;     PG8_WAIT_V(0);
;     if (wr == 0) PG8_BAR;
;     PG8_BAR;
.LBB0_141:
	s_setprio 0
	v_readlane_b32 s24, v237, 4
	v_readlane_b32 s36, v237, 0
	v_readlane_b32 s26, v237, 6
	v_readlane_b32 s27, v237, 7
	v_readlane_b32 s30, v237, 10
	v_readlane_b32 s31, v237, 11
	v_readlane_b32 s37, v237, 1
	v_readlane_b32 s22, v236, 22
	v_readlane_b32 s34, v236, 24
	v_readlane_b32 s36, v236, 26
	v_readlane_b32 s26, v236, 28
	v_readlane_b32 s30, v236, 30
	v_readlane_b32 s20, v236, 32
	v_readlane_b32 s25, v237, 5
	v_readlane_b32 s28, v237, 8
	v_readlane_b32 s29, v237, 9
	v_readlane_b32 s38, v237, 2
	v_readlane_b32 s39, v237, 3
	v_readlane_b32 s58, v236, 21
	v_readlane_b32 s23, v236, 23
	v_readlane_b32 s35, v236, 25
	v_readlane_b32 s37, v236, 27
	v_readlane_b32 s27, v236, 29
	v_readlane_b32 s31, v236, 31
	v_readlane_b32 s21, v236, 33
	s_barrier

; #define PG8_STAGE(bufoff, gbase, voff) do { _Pragma("unroll") for (int _i = 0; _i < 2; ++_i) \
;         __builtin_amdgcn_global_load_lds((const unsigned*)((const char*)(gbase) + (voff)[_i]), (LAS unsigned*)(lds + (bufoff) + ldsw + _i * 8192), 16, 0, 0); } while (0)
; #define PG8_LDA(dst, b, h) do { _Pragma("unroll") for (int m = 0; m < 4; ++m) _Pragma("unroll") for (int k = 0; k < 2; ++k) dst[m][k] = *(const LAS bf16x8*)(lds + PG8_SA(b, h) + aoff + m * 2048 + k * 1024); } while (0)
; #define PG8_BAR __builtin_amdgcn_s_barrier()
; template <bool REMAP>
; DI void gemm_phase(LAS unsigned char* lds, const u16* A, int lda, const u16* Bt, int K, u16* O, int ldc, int nunits) {
;     ...
;     f32x4 acc[2][2][4][2];
; #pragma unroll
;     for (int a = 0; a < 2; ++a)
; #pragma unroll
;         for (int b = 0; b < 2; ++b)
; #pragma unroll
;             for (int m = 0; m < 4; ++m)
; #pragma unroll
;                 for (int n = 0; n < 2; ++n) acc[a][b][m][n] = (f32x4){0.f, 0.f, 0.f, 0.f};
;     bf16x8 At[4][2], B0[2][2], B1[2][2];
;     const char* cA = (const char*)A + (size_t)cur.pm * tstepA; const char* cB = (const char*)Bt + (size_t)cur.pn * tstepB;
;     PG8_STAGE(PG8_SB(0, 0), cB, voffB); PG8_STAGE(PG8_SA(0, 0), cA + akb(0), voffA); PG8_STAGE(PG8_SB(0, 1), cB + hstepB, voffB); PG8_STAGE(PG8_SA(0, 1), cA + akb(0) + hstepA, voffA);
;     if (wr == 1) PG8_BAR;
;     PG8_WAIT_V(4); PG8_BAR;
;     PG8_STAGE(PG8_SB(1, 0), cB + kstep, voffB); PG8_STAGE(PG8_SA(1, 0), cA + akb(1), voffA); PG8_STAGE(PG8_SB(1, 1), cB + hstepB + kstep, voffB);
;     PG8_WAIT_V(6); PG8_BAR;
;     for (;;) {
;         const bool has_next = next_unit(ui + 1, nunits, nxt);
;         const char* nA = has_next ? (const char*)A + (size_t)nxt.pm * tstepA : cA; const char* nB = has_next ? (const char*)Bt + (size_t)nxt.pn * tstepB : cB;
;         for (int t = 0; t < nt; t += 2) {
;             const bool last = (t == nt - 2);
;             const char* a1 = cA + akb(t + 1);
;             const char* a2 = last ? nA + akb(0) : cA + akb(t + 2); const char* b2 = last ? nB : cB + (size_t)(t + 2) * kstep;
;             const char* a3 = last ? nA + akb(1) : cA + akb(t + 3); const char* b3 = b2 + kstep;
;             PG8_LDB(B0, 0, 0); PG8_SCHED; PG8_LDA(At, 0, 0); PG8_STAGE(PG8_SA(1, 1), a1 + hstepA, voffA);
;             PG8_WAIT_L(8); PG8_BAR; PG8_WAIT_L(0); PG8_MMA(0, 0, At, B0); PG8_BAR; PG8_SCHED;
.LBB0_386:
	s_ashr_i32 s5, s4, 31
	s_lshl_b64 s[12:13], s[4:5], 20
	s_add_u32 s12, s24, s12
	s_addc_u32 s13, s25, s13
	s_and_b64 s[14:15], s[14:15], exec
	s_cselect_b32 s5, s13, s21
	s_cselect_b32 s41, s12, s20
	s_add_u32 s14, s10, 0x80
	s_addc_u32 s15, s11, 0
	s_add_u32 s46, s20, 0x100
	v_mov_b32_e32 v2, 0
	s_addc_u32 s47, s21, 0
	s_mov_b32 s50, 0
	s_movk_i32 s49, 0xc0
	v_mov_b32_e32 v3, v2
	v_mov_b32_e32 v4, v2
	v_mov_b32_e32 v5, v2
	v_mov_b32_e32 v6, v2
	v_mov_b32_e32 v7, v2
	v_mov_b32_e32 v8, v2
	v_mov_b32_e32 v9, v2
	v_mov_b32_e32 v10, v2
	v_mov_b32_e32 v11, v2
	v_mov_b32_e32 v12, v2
	v_mov_b32_e32 v13, v2
	v_mov_b32_e32 v14, v2
	v_mov_b32_e32 v15, v2
	v_mov_b32_e32 v16, v2
	v_mov_b32_e32 v17, v2
	v_mov_b32_e32 v26, v2
	v_mov_b32_e32 v27, v2
	v_mov_b32_e32 v28, v2
	v_mov_b32_e32 v29, v2
	v_mov_b32_e32 v30, v2
	v_mov_b32_e32 v31, v2
	v_mov_b32_e32 v32, v2
	v_mov_b32_e32 v33, v2
	v_mov_b32_e32 v42, v2
	v_mov_b32_e32 v43, v2
	v_mov_b32_e32 v44, v2
	v_mov_b32_e32 v45, v2
	v_mov_b32_e32 v46, v2
	v_mov_b32_e32 v47, v2
	v_mov_b32_e32 v48, v2
	v_mov_b32_e32 v49, v2
	v_mov_b32_e32 v18, v2
	v_mov_b32_e32 v19, v2
	v_mov_b32_e32 v20, v2
	v_mov_b32_e32 v21, v2
	v_mov_b32_e32 v22, v2
	v_mov_b32_e32 v23, v2
	v_mov_b32_e32 v24, v2
	v_mov_b32_e32 v25, v2
	v_mov_b32_e32 v34, v2
	v_mov_b32_e32 v35, v2
	v_mov_b32_e32 v36, v2
	v_mov_b32_e32 v37, v2
	v_mov_b32_e32 v38, v2
	v_mov_b32_e32 v39, v2
	v_mov_b32_e32 v40, v2
	v_mov_b32_e32 v41, v2
	v_mov_b32_e32 v50, v2
	v_mov_b32_e32 v51, v2
	v_mov_b32_e32 v52, v2
	v_mov_b32_e32 v53, v2
	v_mov_b32_e32 v54, v2
	v_mov_b32_e32 v55, v2
	v_mov_b32_e32 v56, v2
	v_mov_b32_e32 v57, v2
	v_mov_b32_e32 v58, v2
	v_mov_b32_e32 v59, v2
	v_mov_b32_e32 v60, v2
	v_mov_b32_e32 v61, v2
	v_mov_b32_e32 v62, v2
	v_mov_b32_e32 v63, v2
	v_mov_b32_e32 v64, v2
	v_mov_b32_e32 v65, v2
	v_mov_b32_e32 v66, v2
	v_mov_b32_e32 v67, v2
	v_mov_b32_e32 v68, v2
	v_mov_b32_e32 v69, v2
	v_mov_b32_e32 v70, v2
	v_mov_b32_e32 v71, v2
	v_mov_b32_e32 v72, v2
	v_mov_b32_e32 v73, v2
	v_mov_b32_e32 v74, v2
	v_mov_b32_e32 v75, v2
	v_mov_b32_e32 v76, v2
	v_mov_b32_e32 v77, v2
	v_mov_b32_e32 v78, v2
	v_mov_b32_e32 v79, v2
	v_mov_b32_e32 v80, v2
	v_mov_b32_e32 v81, v2
	v_mov_b32_e32 v90, v2
	v_mov_b32_e32 v91, v2
	v_mov_b32_e32 v92, v2
	v_mov_b32_e32 v93, v2
	v_mov_b32_e32 v94, v2
	v_mov_b32_e32 v95, v2
	v_mov_b32_e32 v96, v2
	v_mov_b32_e32 v97, v2
	v_mov_b32_e32 v106, v2
	v_mov_b32_e32 v107, v2
	v_mov_b32_e32 v108, v2
	v_mov_b32_e32 v109, v2
	v_mov_b32_e32 v110, v2
	v_mov_b32_e32 v111, v2
	v_mov_b32_e32 v112, v2
	v_mov_b32_e32 v113, v2
	v_mov_b32_e32 v82, v2
	v_mov_b32_e32 v83, v2
	v_mov_b32_e32 v84, v2
	v_mov_b32_e32 v85, v2
	v_mov_b32_e32 v86, v2
	v_mov_b32_e32 v87, v2
	v_mov_b32_e32 v88, v2
	v_mov_b32_e32 v89, v2
	v_mov_b32_e32 v98, v2
	v_mov_b32_e32 v99, v2
	v_mov_b32_e32 v100, v2
	v_mov_b32_e32 v101, v2
	v_mov_b32_e32 v102, v2
	v_mov_b32_e32 v103, v2
	v_mov_b32_e32 v104, v2
	v_mov_b32_e32 v105, v2
	v_mov_b32_e32 v114, v2
	v_mov_b32_e32 v115, v2
	v_mov_b32_e32 v116, v2
	v_mov_b32_e32 v117, v2
	v_mov_b32_e32 v118, v2
	v_mov_b32_e32 v119, v2
	v_mov_b32_e32 v120, v2
	v_mov_b32_e32 v121, v2
	v_mov_b32_e32 v122, v2
	v_mov_b32_e32 v123, v2
	v_mov_b32_e32 v124, v2
	v_mov_b32_e32 v125, v2
	v_mov_b32_e32 v126, v2
	v_mov_b32_e32 v127, v2
	v_mov_b32_e32 v128, v2
	v_mov_b32_e32 v129, v2
	s_cmp_ge_u32 s27, 0x1000
	s_cbranch_scc0 .Lg2_noprio
	s_setprio 1
.Lg2_noprio:
	s_branch .LBB0_388
.LBB0_387:
	s_and_b64 s[20:21], exec, s[20:21]
	s_cselect_b32 s21, s5, s47
	s_cselect_b32 s20, s41, s46
	s_cmp_lt_u32 s50, 24
	s_cselect_b32 s51, 0x180, s68
	s_cmp_gt_u32 s50, 11
	s_cselect_b32 s51, s51, 0
	s_add_i32 s51, s51, s49
	s_lshl_b32 s51, s51, 1
	s_addk_i32 s51, 0xff00
	s_add_u32 s51, s6, s51
	s_addc_u32 s55, s7, 0
	s_add_i32 s56, 0, 0x10000
	v_add_u32_e32 v152, s56, v137
	ds_read_b128 v[140:143], v152
	ds_read_b128 v[144:147], v152 offset:1024
	ds_read_b128 v[148:151], v152 offset:2048
	ds_read_b128 v[152:155], v152 offset:3072
	s_add_u32 s54, s51, 0x1c0000
	s_addc_u32 s55, s55, 0
	v_lshl_add_u64 v[172:173], s[54:55], 0, v[134:135]
	s_add_i32 m0, s27, 0xc000
	ds_read_b128 v[156:159], v139
	ds_read_b128 v[160:163], v139 offset:1024
	ds_read_b128 v[164:167], v139 offset:2048
	ds_read_b128 v[168:171], v139 offset:3072
	ds_read_b128 v[192:195], v139 offset:4096
	ds_read_b128 v[196:199], v139 offset:5120
	ds_read_b128 v[200:203], v139 offset:6144
	ds_read_b128 v[204:207], v139 offset:7168
	global_load_lds_dwordx4 v[172:173], off
	v_lshl_add_u64 v[172:173], s[54:55], 0, v[132:133]
	s_add_i32 m0, s27, 0xe000
	s_nop 0
	global_load_lds_dwordx4 v[172:173], off
	s_waitcnt lgkmcnt(8)
	s_barrier
	s_waitcnt lgkmcnt(0)
	s_waitcnt lgkmcnt(0)
	v_mfma_f32_16x16x32_bf16 v[126:129], v[140:143], v[156:159], v[126:129]
	v_mfma_f32_16x16x32_bf16 v[122:125], v[148:151], v[156:159], v[122:125]
	v_mfma_f32_16x16x32_bf16 v[118:121], v[140:143], v[164:167], v[118:121]
	v_mfma_f32_16x16x32_bf16 v[114:117], v[148:151], v[164:167], v[114:117]
	v_mfma_f32_16x16x32_bf16 v[102:105], v[140:143], v[192:195], v[102:105]
	v_mfma_f32_16x16x32_bf16 v[98:101], v[148:151], v[192:195], v[98:101]
	v_mfma_f32_16x16x32_bf16 v[86:89], v[140:143], v[200:203], v[86:89]
	v_mfma_f32_16x16x32_bf16 v[82:85], v[148:151], v[200:203], v[82:85]
	v_mfma_f32_16x16x32_bf16 v[126:129], v[144:147], v[160:163], v[126:129]
	v_mfma_f32_16x16x32_bf16 v[122:125], v[152:155], v[160:163], v[122:125]
	v_mfma_f32_16x16x32_bf16 v[118:121], v[144:147], v[168:171], v[118:121]
	v_mfma_f32_16x16x32_bf16 v[114:117], v[152:155], v[168:171], v[114:117]
	v_mfma_f32_16x16x32_bf16 v[102:105], v[144:147], v[196:199], v[102:105]
	v_mfma_f32_16x16x32_bf16 v[98:101], v[152:155], v[196:199], v[98:101]
	v_mfma_f32_16x16x32_bf16 v[86:89], v[144:147], v[204:207], v[86:89]
	v_mfma_f32_16x16x32_bf16 v[82:85], v[152:155], v[204:207], v[82:85]
	s_barrier
; #define PG8_STAGE(bufoff, gbase, voff) do { _Pragma("unroll") for (int _i = 0; _i < 2; ++_i) \
;         __builtin_amdgcn_global_load_lds((const unsigned*)((const char*)(gbase) + (voff)[_i]), (LAS unsigned*)(lds + (bufoff) + ldsw + _i * 8192), 16, 0, 0); } while (0)
; #define PG8_LDA(dst, b, h) do { _Pragma("unroll") for (int m = 0; m < 4; ++m) _Pragma("unroll") for (int k = 0; k < 2; ++k) dst[m][k] = *(const LAS bf16x8*)(lds + PG8_SA(b, h) + aoff + m * 2048 + k * 1024); } while (0)
; #define PG8_LDB(dst, b, h) do { _Pragma("unroll") for (int n = 0; n < 2; ++n) _Pragma("unroll") for (int k = 0; k < 2; ++k) dst[n][k] = *(const LAS bf16x8*)(lds + PG8_SB(b, h) + boff + n * 2048 + k * 1024); } while (0)
; #define PG8_MMA(ai, bj, At, Bt_) do { __builtin_amdgcn_s_setprio(1); _Pragma("unroll") for (int m = 0; m < 4; ++m) _Pragma("unroll") for (int n = 0; n < 2; ++n) _Pragma("unroll") for (int k = 0; k < 2; ++k) \
;         acc[ai][bj][m][n] = __builtin_amdgcn_mfma_f32_16x16x32_bf16(Bt_[n][k], At[m][k], acc[ai][bj][m][n], 0, 0, 0); __builtin_amdgcn_s_setprio(0); } while (0)
; #define PG8_WAIT_V(n) asm volatile("s_waitcnt vmcnt(" #n ")" ::: "memory")
; #define PG8_WAIT_L(n) asm volatile("s_waitcnt lgkmcnt(" #n ")" ::: "memory")
; #define PG8_BAR __builtin_amdgcn_s_barrier()
; #define PG8_SCHED __builtin_amdgcn_sched_barrier(0)
; template <bool REMAP>
; DI void gemm_phase(LAS unsigned char* lds, const u16* A, int lda, const u16* Bt, int K, u16* O, int ldc, int nunits) {
;     ...
;             PG8_LDB(B1, 0, 1); PG8_STAGE(PG8_SB(0, 0), b2, voffB);
;             PG8_BAR; PG8_WAIT_L(0); PG8_MMA(0, 1, At, B1); PG8_BAR;
;             PG8_LDA(At, 0, 1); PG8_STAGE(PG8_SA(0, 0), a2, voffA);
;             PG8_BAR; PG8_WAIT_L(0); PG8_MMA(1, 0, At, B0); PG8_BAR; PG8_SCHED;
;             PG8_STAGE(PG8_SB(0, 1), b2 + hstepB, voffB);
;             PG8_WAIT_V(6); PG8_BAR; PG8_MMA(1, 1, At, B1); PG8_BAR;
;             PG8_LDB(B0, 1, 0); PG8_SCHED; PG8_LDA(At, 1, 0); PG8_STAGE(PG8_SA(0, 1), a2 + hstepA, voffA);
	s_add_i32 s51, 0, 0x14000
	v_add_u32_e32 v172, s51, v137
	s_add_i32 s54, s56, s26
	ds_read_b128 v[208:211], v172
	ds_read_b128 v[212:215], v172 offset:1024
	ds_read_b128 v[216:219], v172 offset:2048
	ds_read_b128 v[220:223], v172 offset:3072
	v_lshl_add_u64 v[172:173], s[20:21], 0, v[0:1]
	s_mov_b32 m0, s54
	v_lshl_add_u64 v[224:225], s[20:21], 0, v[130:131]
	global_load_lds_dwordx4 v[172:173], off
	s_add_i32 m0, s54, 0x2000
	s_nop 0
	global_load_lds_dwordx4 v[224:225], off
	s_barrier
	s_waitcnt lgkmcnt(0)
	s_waitcnt lgkmcnt(0)
	v_mfma_f32_16x16x32_bf16 v[110:113], v[208:211], v[156:159], v[110:113]
	v_mfma_f32_16x16x32_bf16 v[106:109], v[216:219], v[156:159], v[106:109]
	v_mfma_f32_16x16x32_bf16 v[94:97], v[208:211], v[164:167], v[94:97]
	v_mfma_f32_16x16x32_bf16 v[90:93], v[216:219], v[164:167], v[90:93]
	v_mfma_f32_16x16x32_bf16 v[78:81], v[208:211], v[192:195], v[78:81]
	v_mfma_f32_16x16x32_bf16 v[74:77], v[216:219], v[192:195], v[74:77]
	v_mfma_f32_16x16x32_bf16 v[70:73], v[208:211], v[200:203], v[70:73]
	v_mfma_f32_16x16x32_bf16 v[66:69], v[216:219], v[200:203], v[66:69]
	v_mfma_f32_16x16x32_bf16 v[110:113], v[212:215], v[160:163], v[110:113]
	v_mfma_f32_16x16x32_bf16 v[106:109], v[220:223], v[160:163], v[106:109]
	v_mfma_f32_16x16x32_bf16 v[94:97], v[212:215], v[168:171], v[94:97]
	v_mfma_f32_16x16x32_bf16 v[90:93], v[220:223], v[168:171], v[90:93]
	v_mfma_f32_16x16x32_bf16 v[78:81], v[212:215], v[196:199], v[78:81]
	v_mfma_f32_16x16x32_bf16 v[74:77], v[220:223], v[196:199], v[74:77]
	v_mfma_f32_16x16x32_bf16 v[70:73], v[212:215], v[204:207], v[70:73]
	v_mfma_f32_16x16x32_bf16 v[66:69], v[220:223], v[204:207], v[66:69]
	s_mov_b32 m0, s27
	v_lshl_add_u64 v[226:227], s[28:29], 0, v[134:135]
	s_barrier
	ds_read_b128 v[156:159], v139 offset:16384
	ds_read_b128 v[160:163], v139 offset:17408
	ds_read_b128 v[164:167], v139 offset:18432
	ds_read_b128 v[168:171], v139 offset:19456
	ds_read_b128 v[192:195], v139 offset:20480
	ds_read_b128 v[196:199], v139 offset:21504
	ds_read_b128 v[200:203], v139 offset:22528
	ds_read_b128 v[204:207], v139 offset:23552
	global_load_lds_dwordx4 v[226:227], off
	v_lshl_add_u64 v[226:227], s[28:29], 0, v[132:133]
	s_mov_b32 m0, s30
	s_nop 0
	global_load_lds_dwordx4 v[226:227], off
	s_barrier
	s_waitcnt lgkmcnt(0)
	s_waitcnt lgkmcnt(0)
	v_mfma_f32_16x16x32_bf16 v[62:65], v[140:143], v[156:159], v[62:65]
	v_mfma_f32_16x16x32_bf16 v[58:61], v[148:151], v[156:159], v[58:61]
	v_mfma_f32_16x16x32_bf16 v[54:57], v[140:143], v[164:167], v[54:57]
	v_mfma_f32_16x16x32_bf16 v[50:53], v[148:151], v[164:167], v[50:53]
	v_mfma_f32_16x16x32_bf16 v[38:41], v[140:143], v[192:195], v[38:41]
	v_mfma_f32_16x16x32_bf16 v[34:37], v[148:151], v[192:195], v[34:37]
	v_mfma_f32_16x16x32_bf16 v[22:25], v[140:143], v[200:203], v[22:25]
	v_mfma_f32_16x16x32_bf16 v[18:21], v[148:151], v[200:203], v[18:21]
	v_mfma_f32_16x16x32_bf16 v[62:65], v[144:147], v[160:163], v[62:65]
	v_mfma_f32_16x16x32_bf16 v[58:61], v[152:155], v[160:163], v[58:61]
	v_mfma_f32_16x16x32_bf16 v[54:57], v[144:147], v[168:171], v[54:57]
	v_mfma_f32_16x16x32_bf16 v[50:53], v[152:155], v[168:171], v[50:53]
	v_mfma_f32_16x16x32_bf16 v[38:41], v[144:147], v[196:199], v[38:41]
	v_mfma_f32_16x16x32_bf16 v[34:37], v[152:155], v[196:199], v[34:37]
	v_mfma_f32_16x16x32_bf16 v[22:25], v[144:147], v[204:207], v[22:25]
	v_mfma_f32_16x16x32_bf16 v[18:21], v[152:155], v[204:207], v[18:21]
	s_barrier
	s_add_u32 s54, s20, 0x80000
	s_addc_u32 s55, s21, 0
	s_add_i32 s51, s51, s26
	v_lshl_add_u64 v[140:141], s[54:55], 0, v[0:1]
	s_mov_b32 m0, s51
	s_nop 0
	global_load_lds_dwordx4 v[140:141], off
	v_lshl_add_u64 v[140:141], s[54:55], 0, v[130:131]
	s_add_i32 m0, s51, 0x2000
	s_nop 0
	global_load_lds_dwordx4 v[140:141], off
	s_waitcnt vmcnt(6)
	s_barrier
	v_mfma_f32_16x16x32_bf16 v[46:49], v[208:211], v[156:159], v[46:49]
	v_mfma_f32_16x16x32_bf16 v[42:45], v[216:219], v[156:159], v[42:45]
	v_mfma_f32_16x16x32_bf16 v[30:33], v[208:211], v[164:167], v[30:33]
	v_mfma_f32_16x16x32_bf16 v[26:29], v[216:219], v[164:167], v[26:29]
	v_mfma_f32_16x16x32_bf16 v[14:17], v[208:211], v[192:195], v[14:17]
	v_mfma_f32_16x16x32_bf16 v[10:13], v[216:219], v[192:195], v[10:13]
	v_mfma_f32_16x16x32_bf16 v[6:9], v[208:211], v[200:203], v[6:9]
	v_mfma_f32_16x16x32_bf16 v[2:5], v[216:219], v[200:203], v[2:5]
	v_mfma_f32_16x16x32_bf16 v[46:49], v[212:215], v[160:163], v[46:49]
	v_mfma_f32_16x16x32_bf16 v[42:45], v[220:223], v[160:163], v[42:45]
	v_mfma_f32_16x16x32_bf16 v[30:33], v[212:215], v[168:171], v[30:33]
	v_mfma_f32_16x16x32_bf16 v[26:29], v[220:223], v[168:171], v[26:29]
	v_mfma_f32_16x16x32_bf16 v[14:17], v[212:215], v[196:199], v[14:17]
	v_mfma_f32_16x16x32_bf16 v[10:13], v[220:223], v[196:199], v[10:13]
	v_mfma_f32_16x16x32_bf16 v[6:9], v[212:215], v[204:207], v[6:9]
	v_mfma_f32_16x16x32_bf16 v[2:5], v[220:223], v[204:207], v[2:5]
	s_add_i32 s51, 0, 0x18000
	v_add_u32_e32 v152, s51, v137
	s_barrier
	ds_read_b128 v[140:143], v152
	ds_read_b128 v[144:147], v152 offset:1024
	ds_read_b128 v[148:151], v152 offset:2048
	ds_read_b128 v[152:155], v152 offset:3072
	s_add_u32 s28, s28, 0x1c0000
	s_addc_u32 s29, s29, 0
	s_mov_b32 m0, s31
	v_lshl_add_u64 v[208:209], s[28:29], 0, v[134:135]
	ds_read_b128 v[156:159], v139 offset:32768
	ds_read_b128 v[160:163], v139 offset:33792
	ds_read_b128 v[164:167], v139 offset:34816
	ds_read_b128 v[168:171], v139 offset:35840
	ds_read_b128 v[192:195], v139 offset:36864
	ds_read_b128 v[196:199], v139 offset:37888
	ds_read_b128 v[200:203], v139 offset:38912
	ds_read_b128 v[204:207], v139 offset:39936
	global_load_lds_dwordx4 v[208:209], off
	v_lshl_add_u64 v[208:209], s[28:29], 0, v[132:133]
	s_mov_b32 m0, s34
	s_nop 0
	global_load_lds_dwordx4 v[208:209], off
	s_waitcnt lgkmcnt(8)
	s_barrier
; #define PG8_STAGE(bufoff, gbase, voff) do { _Pragma("unroll") for (int _i = 0; _i < 2; ++_i) \
;         __builtin_amdgcn_global_load_lds((const unsigned*)((const char*)(gbase) + (voff)[_i]), (LAS unsigned*)(lds + (bufoff) + ldsw + _i * 8192), 16, 0, 0); } while (0)
; #define PG8_LDA(dst, b, h) do { _Pragma("unroll") for (int m = 0; m < 4; ++m) _Pragma("unroll") for (int k = 0; k < 2; ++k) dst[m][k] = *(const LAS bf16x8*)(lds + PG8_SA(b, h) + aoff + m * 2048 + k * 1024); } while (0)
; #define PG8_LDB(dst, b, h) do { _Pragma("unroll") for (int n = 0; n < 2; ++n) _Pragma("unroll") for (int k = 0; k < 2; ++k) dst[n][k] = *(const LAS bf16x8*)(lds + PG8_SB(b, h) + boff + n * 2048 + k * 1024); } while (0)
; #define PG8_MMA(ai, bj, At, Bt_) do { __builtin_amdgcn_s_setprio(1); _Pragma("unroll") for (int m = 0; m < 4; ++m) _Pragma("unroll") for (int n = 0; n < 2; ++n) _Pragma("unroll") for (int k = 0; k < 2; ++k) \
;         acc[ai][bj][m][n] = __builtin_amdgcn_mfma_f32_16x16x32_bf16(Bt_[n][k], At[m][k], acc[ai][bj][m][n], 0, 0, 0); __builtin_amdgcn_s_setprio(0); } while (0)
; #define PG8_WAIT_V(n) asm volatile("s_waitcnt vmcnt(" #n ")" ::: "memory")
; #define PG8_WAIT_L(n) asm volatile("s_waitcnt lgkmcnt(" #n ")" ::: "memory")
; #define PG8_BAR __builtin_amdgcn_s_barrier()
; #define PG8_SCHED __builtin_amdgcn_sched_barrier(0)
; template <bool REMAP>
; DI void gemm_phase(LAS unsigned char* lds, const u16* A, int lda, const u16* Bt, int K, u16* O, int ldc, int nunits) {
;     ...
;             PG8_WAIT_L(8); PG8_BAR; PG8_WAIT_L(0); PG8_MMA(0, 0, At, B0); PG8_BAR; PG8_SCHED;
;             PG8_LDB(B1, 1, 1); PG8_STAGE(PG8_SB(1, 0), b3, voffB);
;             PG8_BAR; PG8_WAIT_L(0); PG8_MMA(0, 1, At, B1); PG8_BAR;
;             PG8_LDA(At, 1, 1); PG8_STAGE(PG8_SA(1, 0), a3, voffA);
;             PG8_BAR; PG8_WAIT_L(0); PG8_MMA(1, 0, At, B0); PG8_BAR; PG8_SCHED;
;             PG8_STAGE(PG8_SB(1, 1), b3 + hstepB, voffB);
;             PG8_WAIT_V(6); PG8_BAR; PG8_MMA(1, 1, At, B1); PG8_BAR;
	s_waitcnt lgkmcnt(0)
	s_waitcnt lgkmcnt(0)
	v_mfma_f32_16x16x32_bf16 v[126:129], v[140:143], v[156:159], v[126:129]
	v_mfma_f32_16x16x32_bf16 v[122:125], v[148:151], v[156:159], v[122:125]
	v_mfma_f32_16x16x32_bf16 v[118:121], v[140:143], v[164:167], v[118:121]
	v_mfma_f32_16x16x32_bf16 v[114:117], v[148:151], v[164:167], v[114:117]
	v_mfma_f32_16x16x32_bf16 v[102:105], v[140:143], v[192:195], v[102:105]
	v_mfma_f32_16x16x32_bf16 v[98:101], v[148:151], v[192:195], v[98:101]
	v_mfma_f32_16x16x32_bf16 v[86:89], v[140:143], v[200:203], v[86:89]
	v_mfma_f32_16x16x32_bf16 v[82:85], v[148:151], v[200:203], v[82:85]
	v_mfma_f32_16x16x32_bf16 v[126:129], v[144:147], v[160:163], v[126:129]
	v_mfma_f32_16x16x32_bf16 v[122:125], v[152:155], v[160:163], v[122:125]
	v_mfma_f32_16x16x32_bf16 v[118:121], v[144:147], v[168:171], v[118:121]
	v_mfma_f32_16x16x32_bf16 v[114:117], v[152:155], v[168:171], v[114:117]
	v_mfma_f32_16x16x32_bf16 v[102:105], v[144:147], v[196:199], v[102:105]
	v_mfma_f32_16x16x32_bf16 v[98:101], v[152:155], v[196:199], v[98:101]
	v_mfma_f32_16x16x32_bf16 v[86:89], v[144:147], v[204:207], v[86:89]
	v_mfma_f32_16x16x32_bf16 v[82:85], v[152:155], v[204:207], v[82:85]
	s_barrier
	s_add_i32 s28, 0, 0x1c000
	s_add_i32 s29, s51, s26
	v_add_u32_e32 v220, s28, v137
	v_lshl_add_u64 v[172:173], v[172:173], 0, s[18:19]
	s_mov_b32 m0, s29
	ds_read_b128 v[208:211], v220
	ds_read_b128 v[212:215], v220 offset:1024
	ds_read_b128 v[216:219], v220 offset:2048
	ds_read_b128 v[220:223], v220 offset:3072
	global_load_lds_dwordx4 v[172:173], off
	v_lshl_add_u64 v[172:173], v[224:225], 0, s[18:19]
	s_add_i32 m0, s29, 0x2000
	s_nop 0
	global_load_lds_dwordx4 v[172:173], off
	s_barrier
	s_waitcnt lgkmcnt(0)
	s_waitcnt lgkmcnt(0)
	v_mfma_f32_16x16x32_bf16 v[110:113], v[208:211], v[156:159], v[110:113]
	v_mfma_f32_16x16x32_bf16 v[106:109], v[216:219], v[156:159], v[106:109]
	v_mfma_f32_16x16x32_bf16 v[94:97], v[208:211], v[164:167], v[94:97]
	v_mfma_f32_16x16x32_bf16 v[90:93], v[216:219], v[164:167], v[90:93]
	v_mfma_f32_16x16x32_bf16 v[78:81], v[208:211], v[192:195], v[78:81]
	v_mfma_f32_16x16x32_bf16 v[74:77], v[216:219], v[192:195], v[74:77]
	v_mfma_f32_16x16x32_bf16 v[70:73], v[208:211], v[200:203], v[70:73]
	v_mfma_f32_16x16x32_bf16 v[66:69], v[216:219], v[200:203], v[66:69]
	v_mfma_f32_16x16x32_bf16 v[110:113], v[212:215], v[160:163], v[110:113]
	v_mfma_f32_16x16x32_bf16 v[106:109], v[220:223], v[160:163], v[106:109]
	v_mfma_f32_16x16x32_bf16 v[94:97], v[212:215], v[168:171], v[94:97]
	v_mfma_f32_16x16x32_bf16 v[90:93], v[220:223], v[168:171], v[90:93]
	v_mfma_f32_16x16x32_bf16 v[78:81], v[212:215], v[196:199], v[78:81]
	v_mfma_f32_16x16x32_bf16 v[74:77], v[220:223], v[196:199], v[74:77]
	v_mfma_f32_16x16x32_bf16 v[70:73], v[212:215], v[204:207], v[70:73]
	v_mfma_f32_16x16x32_bf16 v[66:69], v[220:223], v[204:207], v[66:69]
	s_mov_b32 m0, s35
	v_lshl_add_u64 v[172:173], s[22:23], 0, v[134:135]
	s_barrier
	ds_read_b128 v[156:159], v139 offset:49152
	ds_read_b128 v[160:163], v139 offset:50176
	ds_read_b128 v[164:167], v139 offset:51200
	ds_read_b128 v[168:171], v139 offset:52224
	ds_read_b128 v[192:195], v139 offset:53248
	ds_read_b128 v[196:199], v139 offset:54272
	ds_read_b128 v[200:203], v139 offset:55296
	ds_read_b128 v[204:207], v139 offset:56320
	global_load_lds_dwordx4 v[172:173], off
	v_lshl_add_u64 v[172:173], s[22:23], 0, v[132:133]
	s_mov_b32 m0, s36
	s_nop 0
	global_load_lds_dwordx4 v[172:173], off
	s_barrier
	s_waitcnt lgkmcnt(0)
	s_waitcnt lgkmcnt(0)
	v_mfma_f32_16x16x32_bf16 v[62:65], v[140:143], v[156:159], v[62:65]
	v_mfma_f32_16x16x32_bf16 v[58:61], v[148:151], v[156:159], v[58:61]
	v_mfma_f32_16x16x32_bf16 v[54:57], v[140:143], v[164:167], v[54:57]
	v_mfma_f32_16x16x32_bf16 v[50:53], v[148:151], v[164:167], v[50:53]
	v_mfma_f32_16x16x32_bf16 v[38:41], v[140:143], v[192:195], v[38:41]
	v_mfma_f32_16x16x32_bf16 v[34:37], v[148:151], v[192:195], v[34:37]
	v_mfma_f32_16x16x32_bf16 v[22:25], v[140:143], v[200:203], v[22:25]
	v_mfma_f32_16x16x32_bf16 v[18:21], v[148:151], v[200:203], v[18:21]
	v_mfma_f32_16x16x32_bf16 v[62:65], v[144:147], v[160:163], v[62:65]
	v_mfma_f32_16x16x32_bf16 v[58:61], v[152:155], v[160:163], v[58:61]
	v_mfma_f32_16x16x32_bf16 v[54:57], v[144:147], v[168:171], v[54:57]
	v_mfma_f32_16x16x32_bf16 v[50:53], v[152:155], v[168:171], v[50:53]
	v_mfma_f32_16x16x32_bf16 v[38:41], v[144:147], v[196:199], v[38:41]
	v_mfma_f32_16x16x32_bf16 v[34:37], v[152:155], v[196:199], v[34:37]
	v_mfma_f32_16x16x32_bf16 v[22:25], v[144:147], v[204:207], v[22:25]
	v_mfma_f32_16x16x32_bf16 v[18:21], v[152:155], v[204:207], v[18:21]
	s_barrier
	s_add_u32 s20, s20, 0x80080
	s_addc_u32 s21, s21, 0
	s_add_i32 s22, s28, s26
	v_lshl_add_u64 v[140:141], s[20:21], 0, v[0:1]
	s_mov_b32 m0, s22
	s_nop 0
	global_load_lds_dwordx4 v[140:141], off
	v_lshl_add_u64 v[140:141], s[20:21], 0, v[130:131]
	s_add_i32 m0, s22, 0x2000
	s_nop 0
	global_load_lds_dwordx4 v[140:141], off
	s_waitcnt vmcnt(6)
	s_barrier
	v_mfma_f32_16x16x32_bf16 v[46:49], v[208:211], v[156:159], v[46:49]
	v_mfma_f32_16x16x32_bf16 v[42:45], v[216:219], v[156:159], v[42:45]
	v_mfma_f32_16x16x32_bf16 v[30:33], v[208:211], v[164:167], v[30:33]
	v_mfma_f32_16x16x32_bf16 v[26:29], v[216:219], v[164:167], v[26:29]
	v_mfma_f32_16x16x32_bf16 v[14:17], v[208:211], v[192:195], v[14:17]
	v_mfma_f32_16x16x32_bf16 v[10:13], v[216:219], v[192:195], v[10:13]
	v_mfma_f32_16x16x32_bf16 v[6:9], v[208:211], v[200:203], v[6:9]
	v_mfma_f32_16x16x32_bf16 v[2:5], v[216:219], v[200:203], v[2:5]
	v_mfma_f32_16x16x32_bf16 v[46:49], v[212:215], v[160:163], v[46:49]
	v_mfma_f32_16x16x32_bf16 v[42:45], v[220:223], v[160:163], v[42:45]
	v_mfma_f32_16x16x32_bf16 v[30:33], v[212:215], v[168:171], v[30:33]
	v_mfma_f32_16x16x32_bf16 v[26:29], v[220:223], v[168:171], v[26:29]
	v_mfma_f32_16x16x32_bf16 v[14:17], v[212:215], v[196:199], v[14:17]
	v_mfma_f32_16x16x32_bf16 v[10:13], v[220:223], v[196:199], v[10:13]
	v_mfma_f32_16x16x32_bf16 v[6:9], v[212:215], v[204:207], v[6:9]
	v_mfma_f32_16x16x32_bf16 v[2:5], v[220:223], v[204:207], v[2:5]
	s_add_i32 s20, s50, 2
	s_add_u32 s46, s46, 0x100
	s_addc_u32 s47, s47, 0
	s_addk_i32 s49, 0x80
	s_cmp_gt_u32 s50, 29
	s_mov_b32 s50, s20
	s_barrier
	s_cbranch_scc1 .LBB0_381

; #define PG8_WAIT_V(n) asm volatile("s_waitcnt vmcnt(" #n ")" ::: "memory")
; #define PG8_BAR __builtin_amdgcn_s_barrier()
; DI unsigned xb_add(unsigned* p, unsigned v) { return __hip_atomic_fetch_add(p, v, __ATOMIC_RELAXED, __HIP_MEMORY_SCOPE_AGENT); }
; template <bool REMAP>
; DI void gemm_phase(LAS unsigned char* lds, const u16* A, int lda, const u16* Bt, int K, u16* O, int ldc, int nunits) {
;     ...
;     PG8_WAIT_V(0);
;     if (wr == 0) PG8_BAR;
;     PG8_BAR;
; DI void xcd_barrier(const XcdBarrier& b) {
;     asm volatile("s_waitcnt vmcnt(0)" ::: "memory");
;     __syncthreads();
;     if (threadIdx.x == 0) {
;         unsigned* bar = b.bar;
;         __builtin_amdgcn_s_waitcnt(0);
;         unsigned nloc = b.st[0], nx = b.st[1];
;         if (nloc == 0u) { xcd_barrier_complete(bar, b.x, nloc, nx); b.st[0] = nloc; b.st[1] = nx; }
;         const unsigned old = xb_add(&bar[XB_XSUB(b.x)], 1u);
.LBB0_395:
	s_setprio 0
	s_waitcnt vmcnt(0)
	s_waitcnt vmcnt(0) lgkmcnt(0)
	s_barrier
	s_and_saveexec_b64 s[0:1], s[64:65]
	s_cbranch_execz .LBB0_447
	v_mov_b32_e32 v0, s63
	s_waitcnt vmcnt(0) expcnt(0) lgkmcnt(0)
	ds_read_b32 v3, v0
	v_mov_b32_e32 v0, s70
	ds_read_b32 v2, v0
	s_waitcnt lgkmcnt(1)
	v_cmp_ne_u32_e32 vcc, 0, v3
	s_cbranch_vccnz .LBB0_411
	s_mov_b32 s2, 1
	s_branch .LBB0_399
